# speedup vs baseline: 1.0054x; 1.0054x over previous
; #define SCAN_LOAD(R, TOKP) do { const float* _p = (TOKP); \
;     R##nk = *(const f32x4*)(_p + opoff); R##w = *(const f32x4*)(_p + 64 + opoff); R##b = *(const f32x4*)(_p + 128 + opoff); \
;     R##k = *(const f32x4*)(_p + 192 + opoff); R##r = *(const f32x4*)(_p + 256 + opoff); R##v = _p[voff]; } while (0)
; __device__ __forceinline__ void scan_block(const int WV, const Params& P, int layer, int bh, int hv) {
;     ...
;   auto prefetch_partner = [&](int chunk) {
;     const int slot = (chunk & 1) * (SCH * 2);
;     pg1 = __hip_atomic_load(xpart + slot, __ATOMIC_RELAXED, __HIP_MEMORY_SCOPE_AGENT);
;     pg2 = __hip_atomic_load(xpart + slot + 1, __ATOMIC_RELAXED, __HIP_MEMORY_SCOPE_AGENT);
;   };
;     ...
;     if (chunk >= 1) prefetch_partner(chunk - 1);
;     {
;       const float* base = ring + (size_t)buf * SCH * 384;
;       float* yb = ypart + (size_t)buf * (SCH * 512) + yoff;
;       f32x4 Ank, Aw, Ab, Ak, Ar, Bnk, Bw, Bb, Bk, Br; float Av, Bv;
;       SCAN_LOAD(A, base);
; #pragma unroll 2
;       for (int tok = 0; tok < SCH; tok += 2) {
;         SCAN_LOAD(B, base + (tok + 1) * 384);
;         SCAN_STEP(A, yb + tok * 512);
;         SCAN_LOAD(A, base + ((tok + 2) & (SCH - 1)) * 384);
;         SCAN_STEP(B, yb + (tok + 1) * 512);
;       }
.LBB0_295:
.LBB0_296:
	s_not_b32 s20, s22
	s_lshl_b32 s20, s20, 8
	s_and_b32 s20, s20, 0x100
	s_mov_b32 s21, 0
	v_lshl_add_u64 v[254:255], v[26:27], 0, s[20:21]
	s_mul_i32 s13, s23, 0x6000
	v_lshl_or_b32 v18, v53, 2, s13
	ds_read_b128 v[2:5], v18
	ds_read_b128 v[6:9], v18 offset:256
	ds_read_b128 v[10:13], v18 offset:512
	ds_read_b128 v[14:17], v18 offset:768
	v_lshl_add_u32 v74, v56, 2, s13
	ds_read_b128 v[18:21], v18 offset:1024
	ds_read_b32 v75, v74 offset:1280
	v_cndmask_b32_e64 v73, 0, 1, s[8:9]
	v_mul_lo_u32 v74, v73, s79
	v_lshl_add_u32 v72, v73, 15, v57
	v_add_u32_e32 v73, v58, v74
	v_or_b32_e32 v74, v59, v74
	s_mov_b32 s20, -2
.LBB0_297:
	s_cmp_lg_u32 s20, 6
	s_cbranch_scc1 .Lpp_skip
	global_load_dwordx2 v[42:43], v[254:255], off sc1
	global_load_dwordx2 v[44:45], v[254:255], off offset:8 sc1

; #define EPI_CALL(ai, m) epi_block(EPI, g, acc[ai][0][m][0], acc[ai][0][m][1], acc[ai][1][m][0], acc[ai][1][m][1], \
;       brow + ai * HALF + e_wr * 64 + m * 16 + e_fq * 4, tok0, rs, sq);
; __device__ __forceinline__ void epi_block(const int EPI, const GemmArgs& g, f32x4 a00, f32x4 a01, f32x4 a10, f32x4 a11,
;                                           const int fbase, const int tok0, const float (&rs)[4], float (&sq)[4]) {
;     ...
;     } else if (EPI == EPI_RES) {
;       const size_t idx = (size_t)token * D_ + fbase;
;       float4 hv = *(const float4*)(g.h + idx);
;       hv.x += v0; hv.y += v1; hv.z += v2; hv.w += v3;
;       *(float4*)(g.h + idx) = hv;
;       uint2 o; o.x = pack2bf(hv.x, hv.y); o.y = pack2bf(hv.z, hv.w);
;       *(uint2*)(g.outb + idx) = o;
;       sq[q] += (hv.x * hv.x + hv.y * hv.y) + (hv.z * hv.z + hv.w * hv.w);
; __device__ __forceinline__ void gemm_phase(const int WV, const GemmArgs& g, int tile0) {
;     ...
;     EPI_CALL(0, 0) EPI_CALL(0, 1) EPI_CALL(0, 2) EPI_CALL(0, 3)
;     EPI_CALL(1, 0) EPI_CALL(1, 1) EPI_CALL(1, 2) EPI_CALL(1, 3)
.Lres_epi:
	v_lshlrev_b64 v[158:159], 11, v[140:141]
	v_lshl_add_u64 v[158:159], v[158:159], 0, v[148:149]
	v_lshl_add_u64 v[142:143], v[158:159], 2, s[72:73]
	v_lshl_add_u64 v[150:151], v[158:159], 1, s[58:59]
	s_mov_b32 s7, 0
	s_mov_b32 s6, 0x20000
	v_lshl_add_u64 v[144:145], v[142:143], 0, s[6:7]
	s_mov_b32 s6, 0x10000
	v_lshl_add_u64 v[152:153], v[150:151], 0, s[6:7]
	s_mov_b32 s6, 0x100000
	v_lshl_add_u64 v[146:147], v[142:143], 0, s[6:7]
	s_mov_b32 s6, 0x80000
	v_lshl_add_u64 v[154:155], v[150:151], 0, s[6:7]
	s_mov_b32 s6, 0x120000
	v_lshl_add_u64 v[148:149], v[142:143], 0, s[6:7]
	s_mov_b32 s6, 0x90000
	v_lshl_add_u64 v[156:157], v[150:151], 0, s[6:7]
	global_load_dwordx4 v[184:187], v[142:143], off
	global_load_dwordx4 v[188:191], v[144:145], off
	global_load_dwordx4 v[192:195], v[146:147], off
	global_load_dwordx4 v[196:199], v[148:149], off
	global_load_dwordx4 v[200:203], v[142:143], off offset:64
	global_load_dwordx4 v[204:207], v[144:145], off offset:64
	global_load_dwordx4 v[208:211], v[146:147], off offset:64
	global_load_dwordx4 v[212:215], v[148:149], off offset:64
	global_load_dwordx4 v[216:219], v[142:143], off offset:128
	global_load_dwordx4 v[220:223], v[144:145], off offset:128
	global_load_dwordx4 v[224:227], v[146:147], off offset:128
	global_load_dwordx4 v[228:231], v[148:149], off offset:128
	global_load_dwordx4 v[232:235], v[142:143], off offset:192
	global_load_dwordx4 v[236:239], v[144:145], off offset:192
	global_load_dwordx4 v[240:243], v[146:147], off offset:192
	global_load_dwordx4 v[244:247], v[148:149], off offset:192
	v_mov_b32_e32 v158, 0
	v_mov_b32_e32 v159, 0
	v_mov_b32_e32 v160, 0
	v_mov_b32_e32 v161, 0
	s_waitcnt vmcnt(15)
	v_pk_add_f32 v[126:127], v[126:127], v[184:185]
	v_pk_add_f32 v[128:129], v[128:129], v[186:187]
	v_cvt_pk_bf16_f32 v248, v126, v127
	v_cvt_pk_bf16_f32 v249, v128, v129
	global_store_dwordx4 v[142:143], v[126:129], off
	global_store_dwordx2 v[150:151], v[248:249], off
	global_load_dwordx4 v[184:187], v[142:143], off offset:512
	v_pk_mul_f32 v[126:127], v[126:127], v[126:127]
	v_pk_mul_f32 v[128:129], v[128:129], v[128:129]
	v_add_f32_e32 v126, v126, v127
	v_add_f32_e32 v128, v128, v129
	v_add_f32_e32 v126, v126, v128
	v_add_f32_e32 v158, v158, v126
	s_waitcnt vmcnt(17)
	v_pk_add_f32 v[122:123], v[122:123], v[188:189]
	v_pk_add_f32 v[124:125], v[124:125], v[190:191]
	v_cvt_pk_bf16_f32 v248, v122, v123
	v_cvt_pk_bf16_f32 v249, v124, v125
	global_store_dwordx4 v[144:145], v[122:125], off
	global_store_dwordx2 v[152:153], v[248:249], off
	global_load_dwordx4 v[188:191], v[144:145], off offset:512
	v_pk_mul_f32 v[122:123], v[122:123], v[122:123]
	v_pk_mul_f32 v[124:125], v[124:125], v[124:125]
	v_add_f32_e32 v122, v122, v123
	v_add_f32_e32 v124, v124, v125
	v_add_f32_e32 v122, v122, v124
	v_add_f32_e32 v159, v159, v122
	s_waitcnt vmcnt(19)
	v_pk_add_f32 v[118:119], v[118:119], v[192:193]
	v_pk_add_f32 v[120:121], v[120:121], v[194:195]
	v_cvt_pk_bf16_f32 v248, v118, v119
	v_cvt_pk_bf16_f32 v249, v120, v121
	global_store_dwordx4 v[146:147], v[118:121], off
	global_store_dwordx2 v[154:155], v[248:249], off
	global_load_dwordx4 v[192:195], v[146:147], off offset:512
	v_pk_mul_f32 v[118:119], v[118:119], v[118:119]
	v_pk_mul_f32 v[120:121], v[120:121], v[120:121]
	v_add_f32_e32 v118, v118, v119
	v_add_f32_e32 v120, v120, v121
	v_add_f32_e32 v118, v118, v120
	v_add_f32_e32 v160, v160, v118
	s_waitcnt vmcnt(21)
	v_pk_add_f32 v[114:115], v[114:115], v[196:197]
	v_pk_add_f32 v[116:117], v[116:117], v[198:199]
	v_cvt_pk_bf16_f32 v248, v114, v115
	v_cvt_pk_bf16_f32 v249, v116, v117
	global_store_dwordx4 v[148:149], v[114:117], off
	global_store_dwordx2 v[156:157], v[248:249], off
	global_load_dwordx4 v[196:199], v[148:149], off offset:512
	v_pk_mul_f32 v[114:115], v[114:115], v[114:115]
	v_pk_mul_f32 v[116:117], v[116:117], v[116:117]
	v_add_f32_e32 v114, v114, v115
	v_add_f32_e32 v116, v116, v117
	v_add_f32_e32 v114, v114, v116
	v_add_f32_e32 v161, v161, v114
	s_waitcnt vmcnt(23)
	v_pk_add_f32 v[110:111], v[110:111], v[200:201]
	v_pk_add_f32 v[112:113], v[112:113], v[202:203]
	v_cvt_pk_bf16_f32 v248, v110, v111
	v_cvt_pk_bf16_f32 v249, v112, v113
	global_store_dwordx4 v[142:143], v[110:113], off offset:64
	global_store_dwordx2 v[150:151], v[248:249], off offset:32
	global_load_dwordx4 v[200:203], v[142:143], off offset:576
	v_pk_mul_f32 v[110:111], v[110:111], v[110:111]
	v_pk_mul_f32 v[112:113], v[112:113], v[112:113]
	v_add_f32_e32 v110, v110, v111
	v_add_f32_e32 v112, v112, v113
	v_add_f32_e32 v110, v110, v112
	v_add_f32_e32 v158, v158, v110
	s_waitcnt vmcnt(25)
	v_pk_add_f32 v[106:107], v[106:107], v[204:205]
	v_pk_add_f32 v[108:109], v[108:109], v[206:207]
	v_cvt_pk_bf16_f32 v248, v106, v107
	v_cvt_pk_bf16_f32 v249, v108, v109
	global_store_dwordx4 v[144:145], v[106:109], off offset:64
	global_store_dwordx2 v[152:153], v[248:249], off offset:32
	global_load_dwordx4 v[204:207], v[144:145], off offset:576
	v_pk_mul_f32 v[106:107], v[106:107], v[106:107]
	v_pk_mul_f32 v[108:109], v[108:109], v[108:109]
	v_add_f32_e32 v106, v106, v107
	v_add_f32_e32 v108, v108, v109
	v_add_f32_e32 v106, v106, v108
	v_add_f32_e32 v159, v159, v106
	s_waitcnt vmcnt(27)
	v_pk_add_f32 v[102:103], v[102:103], v[208:209]
	v_pk_add_f32 v[104:105], v[104:105], v[210:211]
	v_cvt_pk_bf16_f32 v248, v102, v103
	v_cvt_pk_bf16_f32 v249, v104, v105
	global_store_dwordx4 v[146:147], v[102:105], off offset:64
	global_store_dwordx2 v[154:155], v[248:249], off offset:32
	global_load_dwordx4 v[208:211], v[146:147], off offset:576
	v_pk_mul_f32 v[102:103], v[102:103], v[102:103]
	v_pk_mul_f32 v[104:105], v[104:105], v[104:105]
	v_add_f32_e32 v102, v102, v103
	v_add_f32_e32 v104, v104, v105
	v_add_f32_e32 v102, v102, v104
	v_add_f32_e32 v160, v160, v102
	s_waitcnt vmcnt(29)
; #define EPI_CALL(ai, m) epi_block(EPI, g, acc[ai][0][m][0], acc[ai][0][m][1], acc[ai][1][m][0], acc[ai][1][m][1], \
;       brow + ai * HALF + e_wr * 64 + m * 16 + e_fq * 4, tok0, rs, sq);
; __device__ __forceinline__ void epi_block(const int EPI, const GemmArgs& g, f32x4 a00, f32x4 a01, f32x4 a10, f32x4 a11,
;                                           const int fbase, const int tok0, const float (&rs)[4], float (&sq)[4]) {
;     ...
;     } else if (EPI == EPI_RES) {
;       const size_t idx = (size_t)token * D_ + fbase;
;       float4 hv = *(const float4*)(g.h + idx);
;       hv.x += v0; hv.y += v1; hv.z += v2; hv.w += v3;
;       *(float4*)(g.h + idx) = hv;
;       uint2 o; o.x = pack2bf(hv.x, hv.y); o.y = pack2bf(hv.z, hv.w);
;       *(uint2*)(g.outb + idx) = o;
;       sq[q] += (hv.x * hv.x + hv.y * hv.y) + (hv.z * hv.z + hv.w * hv.w);
; __device__ __forceinline__ void gemm_phase(const int WV, const GemmArgs& g, int tile0) {
;     ...
;     EPI_CALL(0, 0) EPI_CALL(0, 1) EPI_CALL(0, 2) EPI_CALL(0, 3)
;     EPI_CALL(1, 0) EPI_CALL(1, 1) EPI_CALL(1, 2) EPI_CALL(1, 3)
	v_pk_add_f32 v[98:99], v[98:99], v[212:213]
	v_pk_add_f32 v[100:101], v[100:101], v[214:215]
	v_cvt_pk_bf16_f32 v248, v98, v99
	v_cvt_pk_bf16_f32 v249, v100, v101
	global_store_dwordx4 v[148:149], v[98:101], off offset:64
	global_store_dwordx2 v[156:157], v[248:249], off offset:32
	global_load_dwordx4 v[212:215], v[148:149], off offset:576
	v_pk_mul_f32 v[98:99], v[98:99], v[98:99]
	v_pk_mul_f32 v[100:101], v[100:101], v[100:101]
	v_add_f32_e32 v98, v98, v99
	v_add_f32_e32 v100, v100, v101
	v_add_f32_e32 v98, v98, v100
	v_add_f32_e32 v161, v161, v98
	s_waitcnt vmcnt(31)
	v_pk_add_f32 v[94:95], v[94:95], v[216:217]
	v_pk_add_f32 v[96:97], v[96:97], v[218:219]
	v_cvt_pk_bf16_f32 v248, v94, v95
	v_cvt_pk_bf16_f32 v249, v96, v97
	global_store_dwordx4 v[142:143], v[94:97], off offset:128
	global_store_dwordx2 v[150:151], v[248:249], off offset:64
	global_load_dwordx4 v[216:219], v[142:143], off offset:640
	v_pk_mul_f32 v[94:95], v[94:95], v[94:95]
	v_pk_mul_f32 v[96:97], v[96:97], v[96:97]
	v_add_f32_e32 v94, v94, v95
	v_add_f32_e32 v96, v96, v97
	v_add_f32_e32 v94, v94, v96
	v_add_f32_e32 v158, v158, v94
	s_waitcnt vmcnt(33)
	v_pk_add_f32 v[90:91], v[90:91], v[220:221]
	v_pk_add_f32 v[92:93], v[92:93], v[222:223]
	v_cvt_pk_bf16_f32 v248, v90, v91
	v_cvt_pk_bf16_f32 v249, v92, v93
	global_store_dwordx4 v[144:145], v[90:93], off offset:128
	global_store_dwordx2 v[152:153], v[248:249], off offset:64
	global_load_dwordx4 v[220:223], v[144:145], off offset:640
	v_pk_mul_f32 v[90:91], v[90:91], v[90:91]
	v_pk_mul_f32 v[92:93], v[92:93], v[92:93]
	v_add_f32_e32 v90, v90, v91
	v_add_f32_e32 v92, v92, v93
	v_add_f32_e32 v90, v90, v92
	v_add_f32_e32 v159, v159, v90
	s_waitcnt vmcnt(35)
	v_pk_add_f32 v[86:87], v[86:87], v[224:225]
	v_pk_add_f32 v[88:89], v[88:89], v[226:227]
	v_cvt_pk_bf16_f32 v248, v86, v87
	v_cvt_pk_bf16_f32 v249, v88, v89
	global_store_dwordx4 v[146:147], v[86:89], off offset:128
	global_store_dwordx2 v[154:155], v[248:249], off offset:64
	global_load_dwordx4 v[224:227], v[146:147], off offset:640
	v_pk_mul_f32 v[86:87], v[86:87], v[86:87]
	v_pk_mul_f32 v[88:89], v[88:89], v[88:89]
	v_add_f32_e32 v86, v86, v87
	v_add_f32_e32 v88, v88, v89
	v_add_f32_e32 v86, v86, v88
	v_add_f32_e32 v160, v160, v86
	s_waitcnt vmcnt(37)
	v_pk_add_f32 v[82:83], v[82:83], v[228:229]
	v_pk_add_f32 v[84:85], v[84:85], v[230:231]
	v_cvt_pk_bf16_f32 v248, v82, v83
	v_cvt_pk_bf16_f32 v249, v84, v85
	global_store_dwordx4 v[148:149], v[82:85], off offset:128
	global_store_dwordx2 v[156:157], v[248:249], off offset:64
	global_load_dwordx4 v[228:231], v[148:149], off offset:640
	v_pk_mul_f32 v[82:83], v[82:83], v[82:83]
	v_pk_mul_f32 v[84:85], v[84:85], v[84:85]
	v_add_f32_e32 v82, v82, v83
	v_add_f32_e32 v84, v84, v85
	v_add_f32_e32 v82, v82, v84
	v_add_f32_e32 v161, v161, v82
	s_waitcnt vmcnt(39)
	v_pk_add_f32 v[78:79], v[78:79], v[232:233]
	v_pk_add_f32 v[80:81], v[80:81], v[234:235]
	v_cvt_pk_bf16_f32 v248, v78, v79
	v_cvt_pk_bf16_f32 v249, v80, v81
	global_store_dwordx4 v[142:143], v[78:81], off offset:192
	global_store_dwordx2 v[150:151], v[248:249], off offset:96
	global_load_dwordx4 v[232:235], v[142:143], off offset:704
	v_pk_mul_f32 v[78:79], v[78:79], v[78:79]
	v_pk_mul_f32 v[80:81], v[80:81], v[80:81]
	v_add_f32_e32 v78, v78, v79
	v_add_f32_e32 v80, v80, v81
	v_add_f32_e32 v78, v78, v80
	v_add_f32_e32 v158, v158, v78
	s_waitcnt vmcnt(41)
	v_pk_add_f32 v[74:75], v[74:75], v[236:237]
	v_pk_add_f32 v[76:77], v[76:77], v[238:239]
	v_cvt_pk_bf16_f32 v248, v74, v75
	v_cvt_pk_bf16_f32 v249, v76, v77
	global_store_dwordx4 v[144:145], v[74:77], off offset:192
	global_store_dwordx2 v[152:153], v[248:249], off offset:96
	global_load_dwordx4 v[236:239], v[144:145], off offset:704
	v_pk_mul_f32 v[74:75], v[74:75], v[74:75]
	v_pk_mul_f32 v[76:77], v[76:77], v[76:77]
	v_add_f32_e32 v74, v74, v75
	v_add_f32_e32 v76, v76, v77
	v_add_f32_e32 v74, v74, v76
	v_add_f32_e32 v159, v159, v74
	s_waitcnt vmcnt(43)
	v_pk_add_f32 v[70:71], v[70:71], v[240:241]
	v_pk_add_f32 v[72:73], v[72:73], v[242:243]
	v_cvt_pk_bf16_f32 v248, v70, v71
	v_cvt_pk_bf16_f32 v249, v72, v73
	global_store_dwordx4 v[146:147], v[70:73], off offset:192
	global_store_dwordx2 v[154:155], v[248:249], off offset:96
	global_load_dwordx4 v[240:243], v[146:147], off offset:704
	v_pk_mul_f32 v[70:71], v[70:71], v[70:71]
	v_pk_mul_f32 v[72:73], v[72:73], v[72:73]
	v_add_f32_e32 v70, v70, v71
	v_add_f32_e32 v72, v72, v73
	v_add_f32_e32 v70, v70, v72
	v_add_f32_e32 v160, v160, v70
	s_waitcnt vmcnt(45)
	v_pk_add_f32 v[66:67], v[66:67], v[244:245]
	v_pk_add_f32 v[68:69], v[68:69], v[246:247]
	v_cvt_pk_bf16_f32 v248, v66, v67
	v_cvt_pk_bf16_f32 v249, v68, v69
	global_store_dwordx4 v[148:149], v[66:69], off offset:192
	global_store_dwordx2 v[156:157], v[248:249], off offset:96
	global_load_dwordx4 v[244:247], v[148:149], off offset:704
	v_pk_mul_f32 v[66:67], v[66:67], v[66:67]
	v_pk_mul_f32 v[68:69], v[68:69], v[68:69]
	v_add_f32_e32 v66, v66, v67
	v_add_f32_e32 v68, v68, v69
	v_add_f32_e32 v66, v66, v68
	v_add_f32_e32 v161, v161, v66
	s_waitcnt vmcnt(45)
	v_pk_add_f32 v[62:63], v[62:63], v[184:185]
	v_pk_add_f32 v[64:65], v[64:65], v[186:187]
	v_cvt_pk_bf16_f32 v248, v62, v63
	v_cvt_pk_bf16_f32 v249, v64, v65
	global_store_dwordx4 v[142:143], v[62:65], off offset:512
	global_store_dwordx2 v[150:151], v[248:249], off offset:256
	s_nop 0
	v_pk_mul_f32 v[62:63], v[62:63], v[62:63]
	v_pk_mul_f32 v[64:65], v[64:65], v[64:65]
	v_add_f32_e32 v62, v62, v63
	v_add_f32_e32 v64, v64, v65
	v_add_f32_e32 v62, v62, v64
	v_add_f32_e32 v158, v158, v62
	s_waitcnt vmcnt(44)
; #define EPI_CALL(ai, m) epi_block(EPI, g, acc[ai][0][m][0], acc[ai][0][m][1], acc[ai][1][m][0], acc[ai][1][m][1], \
;       brow + ai * HALF + e_wr * 64 + m * 16 + e_fq * 4, tok0, rs, sq);
; __device__ __forceinline__ void epi_block(const int EPI, const GemmArgs& g, f32x4 a00, f32x4 a01, f32x4 a10, f32x4 a11,
;                                           const int fbase, const int tok0, const float (&rs)[4], float (&sq)[4]) {
;     ...
;     } else if (EPI == EPI_RES) {
;       const size_t idx = (size_t)token * D_ + fbase;
;       float4 hv = *(const float4*)(g.h + idx);
;       hv.x += v0; hv.y += v1; hv.z += v2; hv.w += v3;
;       *(float4*)(g.h + idx) = hv;
;       uint2 o; o.x = pack2bf(hv.x, hv.y); o.y = pack2bf(hv.z, hv.w);
;       *(uint2*)(g.outb + idx) = o;
;       sq[q] += (hv.x * hv.x + hv.y * hv.y) + (hv.z * hv.z + hv.w * hv.w);
; __device__ __forceinline__ void gemm_phase(const int WV, const GemmArgs& g, int tile0) {
;     ...
;     EPI_CALL(0, 0) EPI_CALL(0, 1) EPI_CALL(0, 2) EPI_CALL(0, 3)
;     EPI_CALL(1, 0) EPI_CALL(1, 1) EPI_CALL(1, 2) EPI_CALL(1, 3)
	v_pk_add_f32 v[58:59], v[58:59], v[188:189]
	v_pk_add_f32 v[60:61], v[60:61], v[190:191]
	v_cvt_pk_bf16_f32 v248, v58, v59
	v_cvt_pk_bf16_f32 v249, v60, v61
	global_store_dwordx4 v[144:145], v[58:61], off offset:512
	global_store_dwordx2 v[152:153], v[248:249], off offset:256
	s_nop 0
	v_pk_mul_f32 v[58:59], v[58:59], v[58:59]
	v_pk_mul_f32 v[60:61], v[60:61], v[60:61]
	v_add_f32_e32 v58, v58, v59
	v_add_f32_e32 v60, v60, v61
	v_add_f32_e32 v58, v58, v60
	v_add_f32_e32 v159, v159, v58
	s_waitcnt vmcnt(43)
	v_pk_add_f32 v[54:55], v[54:55], v[192:193]
	v_pk_add_f32 v[56:57], v[56:57], v[194:195]
	v_cvt_pk_bf16_f32 v248, v54, v55
	v_cvt_pk_bf16_f32 v249, v56, v57
	global_store_dwordx4 v[146:147], v[54:57], off offset:512
	global_store_dwordx2 v[154:155], v[248:249], off offset:256
	s_nop 0
	v_pk_mul_f32 v[54:55], v[54:55], v[54:55]
	v_pk_mul_f32 v[56:57], v[56:57], v[56:57]
	v_add_f32_e32 v54, v54, v55
	v_add_f32_e32 v56, v56, v57
	v_add_f32_e32 v54, v54, v56
	v_add_f32_e32 v160, v160, v54
	s_waitcnt vmcnt(42)
	v_pk_add_f32 v[50:51], v[50:51], v[196:197]
	v_pk_add_f32 v[52:53], v[52:53], v[198:199]
	v_cvt_pk_bf16_f32 v248, v50, v51
	v_cvt_pk_bf16_f32 v249, v52, v53
	global_store_dwordx4 v[148:149], v[50:53], off offset:512
	global_store_dwordx2 v[156:157], v[248:249], off offset:256
	s_nop 0
	v_pk_mul_f32 v[50:51], v[50:51], v[50:51]
	v_pk_mul_f32 v[52:53], v[52:53], v[52:53]
	v_add_f32_e32 v50, v50, v51
	v_add_f32_e32 v52, v52, v53
	v_add_f32_e32 v50, v50, v52
	v_add_f32_e32 v161, v161, v50
	s_waitcnt vmcnt(41)
	v_pk_add_f32 v[46:47], v[46:47], v[200:201]
	v_pk_add_f32 v[48:49], v[48:49], v[202:203]
	v_cvt_pk_bf16_f32 v248, v46, v47
	v_cvt_pk_bf16_f32 v249, v48, v49
	global_store_dwordx4 v[142:143], v[46:49], off offset:576
	global_store_dwordx2 v[150:151], v[248:249], off offset:288
	s_nop 0
	v_pk_mul_f32 v[46:47], v[46:47], v[46:47]
	v_pk_mul_f32 v[48:49], v[48:49], v[48:49]
	v_add_f32_e32 v46, v46, v47
	v_add_f32_e32 v48, v48, v49
	v_add_f32_e32 v46, v46, v48
	v_add_f32_e32 v158, v158, v46
	s_waitcnt vmcnt(40)
	v_pk_add_f32 v[42:43], v[42:43], v[204:205]
	v_pk_add_f32 v[44:45], v[44:45], v[206:207]
	v_cvt_pk_bf16_f32 v248, v42, v43
	v_cvt_pk_bf16_f32 v249, v44, v45
	global_store_dwordx4 v[144:145], v[42:45], off offset:576
	global_store_dwordx2 v[152:153], v[248:249], off offset:288
	s_nop 0
	v_pk_mul_f32 v[42:43], v[42:43], v[42:43]
	v_pk_mul_f32 v[44:45], v[44:45], v[44:45]
	v_add_f32_e32 v42, v42, v43
	v_add_f32_e32 v44, v44, v45
	v_add_f32_e32 v42, v42, v44
	v_add_f32_e32 v159, v159, v42
	s_waitcnt vmcnt(39)
	v_pk_add_f32 v[38:39], v[38:39], v[208:209]
	v_pk_add_f32 v[40:41], v[40:41], v[210:211]
	v_cvt_pk_bf16_f32 v248, v38, v39
	v_cvt_pk_bf16_f32 v249, v40, v41
	global_store_dwordx4 v[146:147], v[38:41], off offset:576
	global_store_dwordx2 v[154:155], v[248:249], off offset:288
	s_nop 0
	v_pk_mul_f32 v[38:39], v[38:39], v[38:39]
	v_pk_mul_f32 v[40:41], v[40:41], v[40:41]
	v_add_f32_e32 v38, v38, v39
	v_add_f32_e32 v40, v40, v41
	v_add_f32_e32 v38, v38, v40
	v_add_f32_e32 v160, v160, v38
	s_waitcnt vmcnt(38)
	v_pk_add_f32 v[34:35], v[34:35], v[212:213]
	v_pk_add_f32 v[36:37], v[36:37], v[214:215]
	v_cvt_pk_bf16_f32 v248, v34, v35
	v_cvt_pk_bf16_f32 v249, v36, v37
	global_store_dwordx4 v[148:149], v[34:37], off offset:576
	global_store_dwordx2 v[156:157], v[248:249], off offset:288
	s_nop 0
	v_pk_mul_f32 v[34:35], v[34:35], v[34:35]
	v_pk_mul_f32 v[36:37], v[36:37], v[36:37]
	v_add_f32_e32 v34, v34, v35
	v_add_f32_e32 v36, v36, v37
	v_add_f32_e32 v34, v34, v36
	v_add_f32_e32 v161, v161, v34
	s_waitcnt vmcnt(37)
	v_pk_add_f32 v[30:31], v[30:31], v[216:217]
	v_pk_add_f32 v[32:33], v[32:33], v[218:219]
	v_cvt_pk_bf16_f32 v248, v30, v31
	v_cvt_pk_bf16_f32 v249, v32, v33
	global_store_dwordx4 v[142:143], v[30:33], off offset:640
	global_store_dwordx2 v[150:151], v[248:249], off offset:320
	s_nop 0
	v_pk_mul_f32 v[30:31], v[30:31], v[30:31]
	v_pk_mul_f32 v[32:33], v[32:33], v[32:33]
	v_add_f32_e32 v30, v30, v31
	v_add_f32_e32 v32, v32, v33
	v_add_f32_e32 v30, v30, v32
	v_add_f32_e32 v158, v158, v30
	s_waitcnt vmcnt(36)
	v_pk_add_f32 v[26:27], v[26:27], v[220:221]
	v_pk_add_f32 v[28:29], v[28:29], v[222:223]
	v_cvt_pk_bf16_f32 v248, v26, v27
	v_cvt_pk_bf16_f32 v249, v28, v29
	global_store_dwordx4 v[144:145], v[26:29], off offset:640
	global_store_dwordx2 v[152:153], v[248:249], off offset:320
	s_nop 0
	v_pk_mul_f32 v[26:27], v[26:27], v[26:27]
	v_pk_mul_f32 v[28:29], v[28:29], v[28:29]
	v_add_f32_e32 v26, v26, v27
	v_add_f32_e32 v28, v28, v29
	v_add_f32_e32 v26, v26, v28
	v_add_f32_e32 v159, v159, v26
	s_waitcnt vmcnt(35)
; __device__ __forceinline__ void epi_block(const int EPI, const GemmArgs& g, f32x4 a00, f32x4 a01, f32x4 a10, f32x4 a11,
;                                           const int fbase, const int tok0, const float (&rs)[4], float (&sq)[4]) {
;     ...
;     } else if (EPI == EPI_RES) {
;       const size_t idx = (size_t)token * D_ + fbase;
;       float4 hv = *(const float4*)(g.h + idx);
;       hv.x += v0; hv.y += v1; hv.z += v2; hv.w += v3;
;       *(float4*)(g.h + idx) = hv;
;       uint2 o; o.x = pack2bf(hv.x, hv.y); o.y = pack2bf(hv.z, hv.w);
;       *(uint2*)(g.outb + idx) = o;
;       sq[q] += (hv.x * hv.x + hv.y * hv.y) + (hv.z * hv.z + hv.w * hv.w);
; __device__ __forceinline__ void gemm_phase(const int WV, const GemmArgs& g, int tile0) {
;     ...
;     if (EPI == EPI_RES || EPI == EPI_PLE) {
; #pragma unroll
;       for (int q = 0; q < 4; ++q) {
;         float s = sq[q];
;         s += __shfl_xor(s, 16); s += __shfl_xor(s, 32);
;         if (e_fq == 0) atomicAdd(g.ssq_out + tok0 + (q >> 1) * HALF + (q & 1) * 16, s);
;       }
	v_pk_add_f32 v[22:23], v[22:23], v[224:225]
	v_pk_add_f32 v[24:25], v[24:25], v[226:227]
	v_cvt_pk_bf16_f32 v248, v22, v23
	v_cvt_pk_bf16_f32 v249, v24, v25
	global_store_dwordx4 v[146:147], v[22:25], off offset:640
	global_store_dwordx2 v[154:155], v[248:249], off offset:320
	s_nop 0
	v_pk_mul_f32 v[22:23], v[22:23], v[22:23]
	v_pk_mul_f32 v[24:25], v[24:25], v[24:25]
	v_add_f32_e32 v22, v22, v23
	v_add_f32_e32 v24, v24, v25
	v_add_f32_e32 v22, v22, v24
	v_add_f32_e32 v160, v160, v22
	s_waitcnt vmcnt(34)
	v_pk_add_f32 v[18:19], v[18:19], v[228:229]
	v_pk_add_f32 v[20:21], v[20:21], v[230:231]
	v_cvt_pk_bf16_f32 v248, v18, v19
	v_cvt_pk_bf16_f32 v249, v20, v21
	global_store_dwordx4 v[148:149], v[18:21], off offset:640
	global_store_dwordx2 v[156:157], v[248:249], off offset:320
	s_nop 0
	v_pk_mul_f32 v[18:19], v[18:19], v[18:19]
	v_pk_mul_f32 v[20:21], v[20:21], v[20:21]
	v_add_f32_e32 v18, v18, v19
	v_add_f32_e32 v20, v20, v21
	v_add_f32_e32 v18, v18, v20
	v_add_f32_e32 v161, v161, v18
	s_waitcnt vmcnt(33)
	v_pk_add_f32 v[14:15], v[14:15], v[232:233]
	v_pk_add_f32 v[16:17], v[16:17], v[234:235]
	v_cvt_pk_bf16_f32 v248, v14, v15
	v_cvt_pk_bf16_f32 v249, v16, v17
	global_store_dwordx4 v[142:143], v[14:17], off offset:704
	global_store_dwordx2 v[150:151], v[248:249], off offset:352
	s_nop 0
	v_pk_mul_f32 v[14:15], v[14:15], v[14:15]
	v_pk_mul_f32 v[16:17], v[16:17], v[16:17]
	v_add_f32_e32 v14, v14, v15
	v_add_f32_e32 v16, v16, v17
	v_add_f32_e32 v14, v14, v16
	v_add_f32_e32 v158, v158, v14
	s_waitcnt vmcnt(32)
	v_pk_add_f32 v[10:11], v[10:11], v[236:237]
	v_pk_add_f32 v[12:13], v[12:13], v[238:239]
	v_cvt_pk_bf16_f32 v248, v10, v11
	v_cvt_pk_bf16_f32 v249, v12, v13
	global_store_dwordx4 v[144:145], v[10:13], off offset:704
	global_store_dwordx2 v[152:153], v[248:249], off offset:352
	s_nop 0
	v_pk_mul_f32 v[10:11], v[10:11], v[10:11]
	v_pk_mul_f32 v[12:13], v[12:13], v[12:13]
	v_add_f32_e32 v10, v10, v11
	v_add_f32_e32 v12, v12, v13
	v_add_f32_e32 v10, v10, v12
	v_add_f32_e32 v159, v159, v10
	s_waitcnt vmcnt(31)
	v_pk_add_f32 v[6:7], v[6:7], v[240:241]
	v_pk_add_f32 v[8:9], v[8:9], v[242:243]
	v_cvt_pk_bf16_f32 v248, v6, v7
	v_cvt_pk_bf16_f32 v249, v8, v9
	global_store_dwordx4 v[146:147], v[6:9], off offset:704
	global_store_dwordx2 v[154:155], v[248:249], off offset:352
	s_nop 0
	v_pk_mul_f32 v[6:7], v[6:7], v[6:7]
	v_pk_mul_f32 v[8:9], v[8:9], v[8:9]
	v_add_f32_e32 v6, v6, v7
	v_add_f32_e32 v8, v8, v9
	v_add_f32_e32 v6, v6, v8
	v_add_f32_e32 v160, v160, v6
	s_waitcnt vmcnt(30)
	v_pk_add_f32 v[2:3], v[2:3], v[244:245]
	v_pk_add_f32 v[4:5], v[4:5], v[246:247]
	v_cvt_pk_bf16_f32 v248, v2, v3
	v_cvt_pk_bf16_f32 v249, v4, v5
	global_store_dwordx4 v[148:149], v[2:5], off offset:704
	global_store_dwordx2 v[156:157], v[248:249], off offset:352
	s_nop 0
	v_pk_mul_f32 v[2:3], v[2:3], v[2:3]
	v_pk_mul_f32 v[4:5], v[4:5], v[4:5]
	v_add_f32_e32 v2, v2, v3
	v_add_f32_e32 v4, v4, v5
	v_add_f32_e32 v2, v2, v4
	v_add_f32_e32 v161, v161, v2
	v_readlane_b32 s4, v250, 43
	v_readlane_b32 s5, v250, 44
	v_cmp_eq_u32_e32 vcc, 0, v183
	ds_bpermute_b32 v0, v163, v158
	s_waitcnt lgkmcnt(0)
	v_add_f32_e32 v0, v158, v0
	ds_bpermute_b32 v4, v164, v0
	v_lshl_add_u64 v[2:3], v[140:141], 2, s[4:5]
	s_and_saveexec_b64 s[8:9], vcc
	s_cbranch_execz .Lres_t0
	s_waitcnt lgkmcnt(0)
	v_add_f32_e32 v0, v0, v4
	global_atomic_add_f32 v[2:3], v0, off
.Lres_t0:
	s_or_b64 exec, exec, s[8:9]
	ds_bpermute_b32 v0, v163, v159
	s_waitcnt lgkmcnt(0)
	v_add_f32_e32 v0, v159, v0
	ds_bpermute_b32 v4, v164, v0
	s_and_saveexec_b64 s[8:9], vcc
	s_cbranch_execz .Lres_t1
	s_waitcnt lgkmcnt(0)
	v_add_f32_e32 v0, v0, v4
	global_atomic_add_f32 v[2:3], v0, off offset:64
.Lres_t1:
	s_or_b64 exec, exec, s[8:9]
	ds_bpermute_b32 v0, v163, v160
	s_waitcnt lgkmcnt(0)
	v_add_f32_e32 v0, v160, v0
	ds_bpermute_b32 v4, v164, v0
	s_and_saveexec_b64 s[8:9], vcc
	s_cbranch_execz .Lres_t2
	s_waitcnt lgkmcnt(0)
	v_add_f32_e32 v0, v0, v4
	global_atomic_add_f32 v[2:3], v0, off offset:512
.Lres_t2:
	s_or_b64 exec, exec, s[8:9]
	ds_bpermute_b32 v0, v163, v161
	s_waitcnt lgkmcnt(0)
	v_add_f32_e32 v0, v161, v0
	ds_bpermute_b32 v4, v164, v0
	s_and_saveexec_b64 s[8:9], vcc
	s_cbranch_execz .Lres_t3
	s_waitcnt lgkmcnt(0)
	v_add_f32_e32 v0, v0, v4
	global_atomic_add_f32 v[2:3], v0, off offset:576

; #define EPI_CALL(ai, m) epi_block(EPI, g, acc[ai][0][m][0], acc[ai][0][m][1], acc[ai][1][m][0], acc[ai][1][m][1], \
;       brow + ai * HALF + e_wr * 64 + m * 16 + e_fq * 4, tok0, rs, sq);
; __device__ __forceinline__ void gemm_phase(const int WV, const GemmArgs& g, int tile0) {
;     ...
;     const int e_wr = tid2 >> 8, e_wc = (tid2 >> 6) & 3, e_fr = tid2 & 15, e_fq = (tid2 >> 4) & 3;
;     const int tok0 = bcol + e_wc * 32 + e_fr;
;     float rs[4] = {1.f, 1.f, 1.f, 1.f}, sq[4] = {0.f, 0.f, 0.f, 0.f};
;     if (EPI == EPI_IN || EPI == EPI_FF1 || EPI == EPI_PLE) {
; #pragma unroll
;       for (int q = 0; q < 4; ++q) rs[q] = rsqrtf(g.ssq_in[tok0 + (q >> 1) * HALF + (q & 1) * 16] * (1.f / D_) + NEPS);
;     }
;     ...
;     EPI_CALL(0, 0) EPI_CALL(0, 1) EPI_CALL(0, 2) EPI_CALL(0, 3)
;     EPI_CALL(1, 0) EPI_CALL(1, 1) EPI_CALL(1, 2) EPI_CALL(1, 3)
.LBB0_446:
	v_bfe_u32 v183, v0, 4, 2
	v_ashrrev_i32_e32 v0, 2, v0
	v_and_b32_e32 v142, 0xffffffc0, v0
	v_add_u32_e32 v143, s50, v142
	v_lshlrev_b32_e32 v0, 2, v183
	v_or_b32_e32 v148, v143, v0
	v_ashrrev_i32_e32 v149, 31, v148
	s_cmp_eq_u32 s55, 1
	s_cbranch_scc1 .Lres_epi
	v_cmp_gt_i32_e64 s[10:11], s77, v148
	v_cmp_lt_i32_e64 s[8:9], s60, v148
	s_cmp_lt_i32 s55, 3
	s_mov_b64 s[12:13], -1
	s_cbranch_scc1 .LBB0_452
	s_cmp_gt_i32 s55, 3
	s_cbranch_scc0 .LBB0_449
	v_lshlrev_b64 v[150:151], 11, v[140:141]
	v_lshl_add_u64 v[154:155], v[150:151], 0, v[148:149]
	v_lshl_add_u64 v[156:157], v[154:155], 2, s[72:73]
	v_lshlrev_b64 v[154:155], 1, v[154:155]
	v_lshl_add_u64 v[158:159], s[40:41], 0, v[154:155]
	global_load_dwordx4 v[150:153], v[156:157], off
	v_mul_f32_e32 v143, 0xbfb8aa3b, v146
	global_load_dwordx2 v[158:159], v[158:159], off
	v_mul_f32_e32 v160, v126, v143
	v_mul_f32_e32 v161, v127, v143
	v_mul_f32_e32 v184, v128, v143
	v_mul_f32_e32 v143, v129, v143
	v_exp_f32_e32 v160, v160
	v_exp_f32_e32 v161, v161
	v_exp_f32_e32 v184, v184
	v_exp_f32_e32 v143, v143
	v_add_f32_e32 v160, 1.0, v160
	v_add_f32_e32 v161, 1.0, v161
	v_add_f32_e32 v185, 1.0, v184
	v_add_f32_e32 v143, 1.0, v143
	v_rcp_f32_e32 v160, v160
	v_rcp_f32_e32 v184, v161
	v_rcp_f32_e32 v161, v185
	v_rcp_f32_e32 v185, v143
	v_lshl_add_u64 v[154:155], s[58:59], 0, v[154:155]
	s_mov_b64 s[12:13], 0
	s_waitcnt vmcnt(1)
	v_mov_b32_e32 v186, v150
	v_mov_b32_e32 v187, v152
	v_mov_b32_e32 v152, v151
	s_waitcnt vmcnt(0)
	v_lshlrev_b32_e32 v151, 16, v159
	v_lshlrev_b32_e32 v150, 16, v158
	v_and_b32_e32 v159, 0xffff0000, v159
	v_and_b32_e32 v158, 0xffff0000, v158
	v_pk_fma_f32 v[160:161], v[160:161], v[150:151], v[186:187]
	v_pk_fma_f32 v[158:159], v[184:185], v[158:159], v[152:153]
	v_mov_b32_e32 v150, v160
	v_mov_b32_e32 v151, v158
	v_mov_b32_e32 v152, v161
	v_mov_b32_e32 v153, v159
	v_cvt_pk_bf16_f32 v184, v160, v158
	v_cvt_pk_bf16_f32 v185, v161, v159
	v_pk_mul_f32 v[158:159], v[158:159], v[158:159]
	global_store_dwordx4 v[156:157], v[150:153], off
	global_store_dwordx2 v[154:155], v[184:185], off
	s_nop 0
	v_pk_fma_f32 v[150:151], v[160:161], v[160:161], v[158:159]
	s_nop 0
	v_add_f32_e32 v143, v150, v151

; __global__ void __launch_bounds__(512) fwd_megakernel(Params P) {
;   cg::grid_group grid = cg::this_grid();
;   char* ws = P.ws;
;   const int WV = __builtin_amdgcn_readfirstlane(threadIdx.x >> 6);
	.amdhsa_kernel _Z14fwd_megakernel6Params
		.amdhsa_group_segment_fixed_size 131076
		.amdhsa_private_segment_fixed_size 0
		.amdhsa_kernarg_size 480
		.amdhsa_user_sgpr_count 2
		.amdhsa_user_sgpr_dispatch_ptr 0
		.amdhsa_user_sgpr_queue_ptr 0
		.amdhsa_user_sgpr_kernarg_segment_ptr 1
		.amdhsa_user_sgpr_dispatch_id 0
		.amdhsa_user_sgpr_kernarg_preload_length 0
		.amdhsa_user_sgpr_kernarg_preload_offset 0
		.amdhsa_user_sgpr_private_segment_size 0
		.amdhsa_uses_dynamic_stack 0
		.amdhsa_enable_private_segment 0
		.amdhsa_system_sgpr_workgroup_id_x 1
		.amdhsa_system_sgpr_workgroup_id_y 0
		.amdhsa_system_sgpr_workgroup_id_z 0
		.amdhsa_system_sgpr_workgroup_info 0
		.amdhsa_system_vgpr_workitem_id 2
		.amdhsa_next_free_vgpr 256
		.amdhsa_next_free_sgpr 100
		.amdhsa_accum_offset 256
		.amdhsa_reserve_vcc 1
		.amdhsa_float_round_mode_32 0
		.amdhsa_float_round_mode_16_64 0
		.amdhsa_float_denorm_mode_32 3
		.amdhsa_float_denorm_mode_16_64 3
		.amdhsa_dx10_clamp 1
		.amdhsa_ieee_mode 1
		.amdhsa_fp16_overflow 0
		.amdhsa_tg_split 0
		.amdhsa_exception_fp_ieee_invalid_op 0
		.amdhsa_exception_fp_denorm_src 0
		.amdhsa_exception_fp_ieee_div_zero 0
		.amdhsa_exception_fp_ieee_overflow 0
		.amdhsa_exception_fp_ieee_underflow 0
		.amdhsa_exception_fp_ieee_inexact 0
		.amdhsa_exception_int_div_zero 0
	.end_amdhsa_kernel

; __global__ void __launch_bounds__(512) fwd_megakernel(Params P) {
;   cg::grid_group grid = cg::this_grid();
;   char* ws = P.ws;
;   const int WV = __builtin_amdgcn_readfirstlane(threadIdx.x >> 6);
amdhsa.kernels:
  - .agpr_count:     0
    .args:
      - .offset:         0
        .size:           224
        .value_kind:     by_value
      - .offset:         224
        .size:           4
        .value_kind:     hidden_block_count_x
      - .offset:         228
        .size:           4
        .value_kind:     hidden_block_count_y
      - .offset:         232
        .size:           4
        .value_kind:     hidden_block_count_z
      - .offset:         236
        .size:           2
        .value_kind:     hidden_group_size_x
      - .offset:         238
        .size:           2
        .value_kind:     hidden_group_size_y
      - .offset:         240
        .size:           2
        .value_kind:     hidden_group_size_z
      - .offset:         242
        .size:           2
        .value_kind:     hidden_remainder_x
      - .offset:         244
        .size:           2
        .value_kind:     hidden_remainder_y
      - .offset:         246
        .size:           2
        .value_kind:     hidden_remainder_z
      - .offset:         264
        .size:           8
        .value_kind:     hidden_global_offset_x
      - .offset:         272
        .size:           8
        .value_kind:     hidden_global_offset_y
      - .offset:         280
        .size:           8
        .value_kind:     hidden_global_offset_z
      - .offset:         288
        .size:           2
        .value_kind:     hidden_grid_dims
      - .offset:         312
        .size:           8
        .value_kind:     hidden_multigrid_sync_arg
    .group_segment_fixed_size: 131076
    .kernarg_segment_align: 8
    .kernarg_segment_size: 480
    .language:       OpenCL C
    .language_version:
      - 2
      - 0
    .max_flat_workgroup_size: 512
    .name:           _Z14fwd_megakernel6Params
    .private_segment_fixed_size: 0
    .sgpr_count:     106
    .sgpr_spill_count: 212
    .symbol:         _Z14fwd_megakernel6Params.kd
    .uniform_work_group_size: 1
    .uses_dynamic_stack: false
    .vgpr_count:     256
    .vgpr_spill_count: 0
    .wavefront_size: 64
